# ADIFF fast loop: cost-weighted VALU spacing (v_exp counted as 2 issue units when distributing softmax VALU over the MFMA gaps)
# speedup vs baseline: 1.0098x; 1.0098x over previous
; #define LAS __attribute__((address_space(3)))
; __device__ __forceinline__ void diff_attn_phase(const Params& p, LAS unsigned char* lds) {
;     ...
;                 for (int ks = 0; ks < 4; ++ks) kf[ks] = *(const LAS bf16x8*)(Ku + kbase + (kxl ^ (32 * ks)));
;                 bf16x8 P[2][2];
; #pragma unroll
;                 for (int r = 0; r < 2; ++r) {
;                     f32x16 S;
; #pragma unroll
;                     for (int i = 0; i < 16; ++i) S[i] = 0.f;
; #pragma unroll
;                     for (int ks = 0; ks < 4; ++ks) S = __builtin_amdgcn_mfma_f32_32x32x16_bf16(kf[ks], qf[r][ks], S, 0, 0, 0);
;                     S = __builtin_amdgcn_mfma_f32_32x32x16_bf16(kone, qm[r], S, 0, 0, 0);
; #pragma unroll
;                     for (int i = 0; i < 16; ++i) S[i] = __builtin_amdgcn_exp2f(S[i]);
;                     l[r] += sum16(S);
;                     P[r][0] = pack8(S, 0); P[r][1] = pack8(S, 8);
;                 }
; #pragma unroll
;                 for (int t = 0; t < 4; ++t) {
;                     const LAS unsigned char* a0 = Vu + (vb0l ^ (64 * t)); const LAS unsigned char* a1 = Vu + (vb1l ^ (64 * t));
;                     const bf16x8 v0 = tr_pair(a0, a1), v1 = tr_pair(a0 + 4096, a1 + 4096);
;                     O[0][t] = __builtin_amdgcn_mfma_f32_32x32x16_bf16(v0, P[0][0], O[0][t], 0, 0, 0);
;                     O[1][t] = __builtin_amdgcn_mfma_f32_32x32x16_bf16(v0, P[1][0], O[1][t], 0, 0, 0);
;                     O[0][t] = __builtin_amdgcn_mfma_f32_32x32x16_bf16(v1, P[0][1], O[0][t], 0, 0, 0);
;                     O[1][t] = __builtin_amdgcn_mfma_f32_32x32x16_bf16(v1, P[1][1], O[1][t], 0, 0, 0);
.Lfb_loopF:
	s_waitcnt lgkmcnt(3)
	v_mfma_f32_32x32x16_bf16 v[146:161], v[198:201], v[166:169], 0
	v_exp_f32_e32 v138, v138
	v_exp_f32_e32 v139, v139
	v_exp_f32_e32 v140, v140
	v_exp_f32_e32 v141, v141
	s_waitcnt lgkmcnt(2)
	v_mfma_f32_32x32x16_bf16 v[146:161], v[202:205], v[170:173], v[146:161]
	v_add_f32_e32 v212, v212, v138
	v_add_f32_e32 v212, v212, v139
	v_add_f32_e32 v212, v212, v140
	v_add_f32_e32 v212, v212, v141
	v_exp_f32_e32 v142, v142
	v_exp_f32_e32 v143, v143
	s_waitcnt lgkmcnt(1)
	v_mfma_f32_32x32x16_bf16 v[146:161], v[208:211], v[174:177], v[146:161]
	v_exp_f32_e32 v144, v144
	v_exp_f32_e32 v145, v145
	v_add_f32_e32 v212, v212, v142
	v_add_f32_e32 v212, v212, v143
	s_waitcnt lgkmcnt(0)
	v_mfma_f32_32x32x16_bf16 v[146:161], v[230:233], v[178:181], v[146:161]
	v_add_f32_e32 v212, v212, v144
	v_add_f32_e32 v212, v212, v145
	v_cvt_pk_bf16_f32 v226, v138, v139
	v_cvt_pk_bf16_f32 v227, v140, v141
	v_cvt_pk_bf16_f32 v228, v142, v143
	v_cvt_pk_bf16_f32 v229, v144, v145
	v_mfma_f32_32x32x16_bf16 v[130:145], v[198:201], v[182:185], 0
	ds_read_b64_tr_b16 v[198:199], v234 offset:16384
	ds_read_b64_tr_b16 v[200:201], v235 offset:16384
	v_mfma_f32_32x32x16_bf16 v[130:145], v[202:205], v[186:189], v[130:145]
	ds_read_b64_tr_b16 v[202:203], v237 offset:16384
	ds_read_b64_tr_b16 v[204:205], v236 offset:16384
	v_exp_f32_e32 v146, v146
	v_exp_f32_e32 v147, v147
	v_exp_f32_e32 v148, v148
	v_mfma_f32_32x32x16_bf16 v[130:145], v[208:211], v[190:193], v[130:145]
	ds_read_b64_tr_b16 v[208:209], v238 offset:16384
	ds_read_b64_tr_b16 v[210:211], v239 offset:16384
	v_exp_f32_e32 v149, v149
	v_add_f32_e32 v213, v213, v146
	v_add_f32_e32 v213, v213, v147
	v_add_f32_e32 v213, v213, v148
	v_mfma_f32_32x32x16_bf16 v[130:145], v[230:233], v[194:197], v[130:145]
	ds_read_b64_tr_b16 v[230:231], v250 offset:16384
	ds_read_b64_tr_b16 v[232:233], v251 offset:16384
	v_add_f32_e32 v213, v213, v149
	v_exp_f32_e32 v150, v150
	v_exp_f32_e32 v151, v151
	s_waitcnt lgkmcnt(6)
	v_mfma_f32_32x32x16_bf16 v[114:129], v[198:201], v[214:217], v[114:129]
	v_exp_f32_e32 v152, v152
	v_exp_f32_e32 v153, v153
	v_mfma_f32_32x32x16_bf16 v[50:65], v[198:201], v[218:221], v[50:65]
	ds_read_b64_tr_b16 v[198:199], v234 offset:20480
	ds_read_b64_tr_b16 v[200:201], v235 offset:20480
	v_add_f32_e32 v213, v213, v150
	v_add_f32_e32 v213, v213, v151
	v_add_f32_e32 v213, v213, v152
	v_add_f32_e32 v213, v213, v153
	s_waitcnt lgkmcnt(6)
	v_mfma_f32_32x32x16_bf16 v[98:113], v[202:205], v[214:217], v[98:113]
	v_exp_f32_e32 v154, v154
	v_exp_f32_e32 v155, v155
	v_mfma_f32_32x32x16_bf16 v[34:49], v[202:205], v[218:221], v[34:49]
	ds_read_b64_tr_b16 v[202:203], v237 offset:20480
	ds_read_b64_tr_b16 v[204:205], v236 offset:20480
	v_exp_f32_e32 v156, v156
	v_exp_f32_e32 v157, v157
	s_waitcnt lgkmcnt(6)
	v_mfma_f32_32x32x16_bf16 v[82:97], v[208:211], v[214:217], v[82:97]
	v_add_f32_e32 v213, v213, v154
	v_add_f32_e32 v213, v213, v155
	v_add_f32_e32 v213, v213, v156
	v_add_f32_e32 v213, v213, v157
	v_mfma_f32_32x32x16_bf16 v[18:33], v[208:211], v[218:221], v[18:33]
	ds_read_b64_tr_b16 v[208:209], v238 offset:20480
	ds_read_b64_tr_b16 v[210:211], v239 offset:20480
	v_exp_f32_e32 v158, v158
	v_exp_f32_e32 v159, v159
	s_waitcnt lgkmcnt(6)
	v_mfma_f32_32x32x16_bf16 v[66:81], v[230:233], v[214:217], v[66:81]
	v_exp_f32_e32 v160, v160
	v_exp_f32_e32 v161, v161
	v_mfma_f32_32x32x16_bf16 v[2:17], v[230:233], v[218:221], v[2:17]
	ds_read_b64_tr_b16 v[230:231], v250 offset:20480
	ds_read_b64_tr_b16 v[232:233], v251 offset:20480
	v_add_f32_e32 v213, v213, v158
	v_add_f32_e32 v213, v213, v159
	v_add_f32_e32 v213, v213, v160
	v_add_f32_e32 v213, v213, v161
	s_cmpk_eq_u32 s29, 0x7f
	s_cbranch_scc1 .Lfb_last0F
	s_cmpk_eq_u32 s29, 0x7e
	s_cbranch_scc1 .Lfb_w0F
	s_waitcnt vmcnt(4)
	s_branch .Lfb_w1F

; __device__ __forceinline__ void diff_attn_phase(const Params& p, LAS unsigned char* lds) {
;     ...
;         auto issue = [&](int ch, int stg) {
;             const char* kg = (const char*)(kp + (tokb + 64 * ch) * ld); const char* vg = (const char*)(vp + (tokb + 64 * ch) * ld);
;             LAS unsigned char* sb = lds + stg * STG;
; #pragma unroll
;             for (int i = 0; i < 2; ++i) { unsigned o = doff[i]; asm volatile("" : "+v"(o));
;                 __builtin_amdgcn_global_load_lds((const void*)(kg + o), (LAS void*)(sb + dlds[i]), 16, 0, 0);
;                 __builtin_amdgcn_global_load_lds((const void*)(vg + o), (LAS void*)(sb + 16384 + dlds[i]), 16, 0, 0); }
;         };
;         issue(0, 0); issue(1, 1);
;         int s_cur = 0, s_nn = 2;
;         for (int ch = 0; ch < NCH; ++ch) {
;             if (ch + 1 < NCH) asm volatile("s_waitcnt vmcnt(4)" ::: "memory"); else asm volatile("s_waitcnt vmcnt(0)" ::: "memory");
;             __builtin_amdgcn_s_barrier(); asm volatile("" ::: "memory");
;             if (ch + 2 < NCH) issue(ch + 2, s_nn);
;             const LAS unsigned char* Ksb = lds + s_cur * STG; const LAS unsigned char* Vsb = Ksb + 16384;
;             s_nn = s_cur; s_cur = (s_cur == 2) ? 0 : s_cur + 1;
; #pragma clang loop unroll(disable)
;             for (int u = 0; u < 2; ++u) {
;                 const LAS unsigned char* Ku = Ksb + u * 8192; const LAS unsigned char* Vu = Vsb + u * 8192;
;                 int kxl = kx, vb0l = vb0, vb1l = vb1; asm volatile("" : "+v"(kxl), "+v"(vb0l), "+v"(vb1l));
;                 bf16x8 kf[4];
; #pragma unroll
;                 for (int ks = 0; ks < 4; ++ks) kf[ks] = *(const LAS bf16x8*)(Ku + kbase + (kxl ^ (32 * ks)));
;                 bf16x8 P[2][2];
; #pragma unroll
;                 for (int r = 0; r < 2; ++r) {
;                     f32x16 S;
; #pragma unroll
;                     for (int i = 0; i < 16; ++i) S[i] = 0.f;
; #pragma unroll
;                     for (int ks = 0; ks < 4; ++ks) S = __builtin_amdgcn_mfma_f32_32x32x16_bf16(kf[ks], qf[r][ks], S, 0, 0, 0);
;                     S = __builtin_amdgcn_mfma_f32_32x32x16_bf16(kone, qm[r], S, 0, 0, 0);
; #pragma unroll
;                     for (int i = 0; i < 16; ++i) S[i] = __builtin_amdgcn_exp2f(S[i]);
;                     l[r] += sum16(S);
;                     P[r][0] = pack8(S, 0); P[r][1] = pack8(S, 8);
;                 }
; #pragma unroll
.Lfb_w1F:
	s_barrier
	s_add_i32 s2, s29, 1
	s_and_b32 s2, s2, 3
	s_mov_b32 s37, 0x8000
	s_cmp_eq_u32 s2, 0
	s_cselect_b32 s37, 0xfffe8000, s37
	v_add_u32_e32 v1, s37, v1
	s_add_i32 s2, s29, 3
	s_lshl_b32 s10, s2, 6
	s_add_u32 s10, s26, s10
	s_addc_u32 s11, s27, 0
	s_lshl_b64 s[10:11], s[10:11], 13
	s_add_u32 s42, s25, s10
	s_addc_u32 s43, s28, s11
	s_add_u32 s10, s22, s10
	s_addc_u32 s11, s23, s11
	s_and_b32 s2, s2, 3
	s_lshl_b32 s2, s2, 15
	s_add_i32 s2, s2, s34
	s_waitcnt lgkmcnt(6)
	v_mfma_f32_32x32x16_bf16 v[114:129], v[198:201], v[222:225], v[114:129]
	v_exp_f32_e32 v130, v130
	v_exp_f32_e32 v131, v131
	v_mfma_f32_32x32x16_bf16 v[50:65], v[198:201], v[226:229], v[50:65]
	v_add_u32_e32 v198, v246, v1
	ds_read_b128 v[198:201], v198
	v_exp_f32_e32 v132, v132
	v_exp_f32_e32 v133, v133
	s_cmpk_gt_u32 s29, 0x7c
	s_cbranch_scc1 .Lfb_nd0F
	s_mov_b32 m0, s2
	s_nop 0
	global_load_lds_dwordx4 v241, s[42:43]
.Lfb_nd0F:
	s_waitcnt lgkmcnt(5)
	v_mfma_f32_32x32x16_bf16 v[98:113], v[202:205], v[222:225], v[98:113]
	v_add_f32_e32 v212, v212, v130
	v_add_f32_e32 v212, v212, v131
	v_add_f32_e32 v212, v212, v132
	v_add_f32_e32 v212, v212, v133
	v_mfma_f32_32x32x16_bf16 v[34:49], v[202:205], v[226:229], v[34:49]
	v_xad_u32 v202, v246, 32, v1
	ds_read_b128 v[202:205], v202
	v_exp_f32_e32 v134, v134
	v_exp_f32_e32 v135, v135
	s_cmpk_gt_u32 s29, 0x7c
	s_cbranch_scc1 .Lfb_nd1F
	s_add_i32 s35, s2, 0x4000
	s_mov_b32 m0, s35
	s_nop 0
	global_load_lds_dwordx4 v241, s[10:11]
.Lfb_nd1F:
	s_waitcnt lgkmcnt(4)
	v_mfma_f32_32x32x16_bf16 v[82:97], v[208:211], v[222:225], v[82:97]
	v_exp_f32_e32 v136, v136
	v_exp_f32_e32 v137, v137
	v_mfma_f32_32x32x16_bf16 v[18:33], v[208:211], v[226:229], v[18:33]
	v_xad_u32 v208, v246, 64, v1
	ds_read_b128 v[208:211], v208
	v_add_f32_e32 v212, v212, v134
	v_add_f32_e32 v212, v212, v135
	v_add_f32_e32 v212, v212, v136
	v_add_f32_e32 v212, v212, v137
	s_cmpk_gt_u32 s29, 0x7c
	s_cbranch_scc1 .Lfb_nd2F
	s_add_i32 s35, s2, 0x2000
	s_mov_b32 m0, s35
	s_nop 0
	global_load_lds_dwordx4 v243, s[42:43]
.Lfb_nd2F:
	s_waitcnt lgkmcnt(3)
	v_mfma_f32_32x32x16_bf16 v[66:81], v[230:233], v[222:225], v[66:81]
	v_cvt_pk_bf16_f32 v214, v146, v147
	v_cvt_pk_bf16_f32 v215, v148, v149
	v_cvt_pk_bf16_f32 v216, v150, v151
	v_cvt_pk_bf16_f32 v217, v152, v153
	v_cvt_pk_bf16_f32 v218, v130, v131
	v_cvt_pk_bf16_f32 v219, v132, v133
	v_cvt_pk_bf16_f32 v220, v134, v135
	v_cvt_pk_bf16_f32 v221, v136, v137
	v_cvt_pk_bf16_f32 v222, v154, v155
	v_cvt_pk_bf16_f32 v223, v156, v157
	v_cvt_pk_bf16_f32 v224, v158, v159
	v_cvt_pk_bf16_f32 v225, v160, v161
	v_mfma_f32_32x32x16_bf16 v[2:17], v[230:233], v[226:229], v[2:17]
	v_xad_u32 v230, v246, s47, v1
	ds_read_b128 v[230:233], v230
	s_cmpk_gt_u32 s29, 0x7c
	s_cbranch_scc1 .Lfb_nd3F
	s_add_i32 s35, s2, 0x6000
	s_mov_b32 m0, s35
	s_nop 0
	global_load_lds_dwordx4 v243, s[10:11]
.Lfb_nd3F:
	s_waitcnt lgkmcnt(3)
	v_mfma_f32_32x32x16_bf16 v[146:161], v[198:201], v[166:169], 0
	v_exp_f32_e32 v138, v138
	v_exp_f32_e32 v139, v139
	v_exp_f32_e32 v140, v140
	v_exp_f32_e32 v141, v141
	s_waitcnt lgkmcnt(2)
	v_mfma_f32_32x32x16_bf16 v[146:161], v[202:205], v[170:173], v[146:161]
	v_add_f32_e32 v212, v212, v138
	v_add_f32_e32 v212, v212, v139
	v_add_f32_e32 v212, v212, v140
	v_add_f32_e32 v212, v212, v141
	v_exp_f32_e32 v142, v142
	v_exp_f32_e32 v143, v143
	s_waitcnt lgkmcnt(1)
	v_mfma_f32_32x32x16_bf16 v[146:161], v[208:211], v[174:177], v[146:161]
	v_exp_f32_e32 v144, v144
	v_exp_f32_e32 v145, v145
	v_add_f32_e32 v212, v212, v142
	v_add_f32_e32 v212, v212, v143
	s_waitcnt lgkmcnt(0)
	v_mfma_f32_32x32x16_bf16 v[146:161], v[230:233], v[178:181], v[146:161]
	v_add_f32_e32 v212, v212, v144
	v_add_f32_e32 v212, v212, v145
	v_cvt_pk_bf16_f32 v226, v138, v139
	v_cvt_pk_bf16_f32 v227, v140, v141
	v_cvt_pk_bf16_f32 v228, v142, v143
	v_cvt_pk_bf16_f32 v229, v144, v145
	v_mfma_f32_32x32x16_bf16 v[130:145], v[198:201], v[182:185], 0
	ds_read_b64_tr_b16 v[198:199], v234 offset:24576
	ds_read_b64_tr_b16 v[200:201], v235 offset:24576
	v_mfma_f32_32x32x16_bf16 v[130:145], v[202:205], v[186:189], v[130:145]
	ds_read_b64_tr_b16 v[202:203], v237 offset:24576
	ds_read_b64_tr_b16 v[204:205], v236 offset:24576
	v_exp_f32_e32 v146, v146
	v_exp_f32_e32 v147, v147
	v_exp_f32_e32 v148, v148
	v_mfma_f32_32x32x16_bf16 v[130:145], v[208:211], v[190:193], v[130:145]
	ds_read_b64_tr_b16 v[208:209], v238 offset:24576
	ds_read_b64_tr_b16 v[210:211], v239 offset:24576
	v_exp_f32_e32 v149, v149
	v_add_f32_e32 v213, v213, v146
	v_add_f32_e32 v213, v213, v147
	v_add_f32_e32 v213, v213, v148
	v_mfma_f32_32x32x16_bf16 v[130:145], v[230:233], v[194:197], v[130:145]
	ds_read_b64_tr_b16 v[230:231], v250 offset:24576
	ds_read_b64_tr_b16 v[232:233], v251 offset:24576
	v_add_f32_e32 v213, v213, v149
	v_exp_f32_e32 v150, v150
	v_exp_f32_e32 v151, v151
	s_waitcnt lgkmcnt(6)
	v_mfma_f32_32x32x16_bf16 v[114:129], v[198:201], v[214:217], v[114:129]
	v_exp_f32_e32 v152, v152
	v_exp_f32_e32 v153, v153
	v_mfma_f32_32x32x16_bf16 v[50:65], v[198:201], v[218:221], v[50:65]
	ds_read_b64_tr_b16 v[198:199], v234 offset:28672
	ds_read_b64_tr_b16 v[200:201], v235 offset:28672
	v_add_f32_e32 v213, v213, v150
	v_add_f32_e32 v213, v213, v151
	v_add_f32_e32 v213, v213, v152
	v_add_f32_e32 v213, v213, v153
	s_waitcnt lgkmcnt(6)
	v_mfma_f32_32x32x16_bf16 v[98:113], v[202:205], v[214:217], v[98:113]
	v_exp_f32_e32 v154, v154
	v_exp_f32_e32 v155, v155
	v_mfma_f32_32x32x16_bf16 v[34:49], v[202:205], v[218:221], v[34:49]
	ds_read_b64_tr_b16 v[202:203], v237 offset:28672
	ds_read_b64_tr_b16 v[204:205], v236 offset:28672
	v_exp_f32_e32 v156, v156
	v_exp_f32_e32 v157, v157
	s_waitcnt lgkmcnt(6)
; #define LAS __attribute__((address_space(3)))
; __device__ __forceinline__ void diff_attn_phase(const Params& p, LAS unsigned char* lds) {
;     ...
;                 for (int ks = 0; ks < 4; ++ks) kf[ks] = *(const LAS bf16x8*)(Ku + kbase + (kxl ^ (32 * ks)));
;                 bf16x8 P[2][2];
; #pragma unroll
;                 for (int r = 0; r < 2; ++r) {
;                     f32x16 S;
; #pragma unroll
;                     for (int i = 0; i < 16; ++i) S[i] = 0.f;
; #pragma unroll
;                     for (int ks = 0; ks < 4; ++ks) S = __builtin_amdgcn_mfma_f32_32x32x16_bf16(kf[ks], qf[r][ks], S, 0, 0, 0);
;                     S = __builtin_amdgcn_mfma_f32_32x32x16_bf16(kone, qm[r], S, 0, 0, 0);
; #pragma unroll
;                     for (int i = 0; i < 16; ++i) S[i] = __builtin_amdgcn_exp2f(S[i]);
;                     l[r] += sum16(S);
;                     P[r][0] = pack8(S, 0); P[r][1] = pack8(S, 8);
;                 }
; #pragma unroll
;                 for (int t = 0; t < 4; ++t) {
;                     const LAS unsigned char* a0 = Vu + (vb0l ^ (64 * t)); const LAS unsigned char* a1 = Vu + (vb1l ^ (64 * t));
;                     const bf16x8 v0 = tr_pair(a0, a1), v1 = tr_pair(a0 + 4096, a1 + 4096);
;                     O[0][t] = __builtin_amdgcn_mfma_f32_32x32x16_bf16(v0, P[0][0], O[0][t], 0, 0, 0);
;                     O[1][t] = __builtin_amdgcn_mfma_f32_32x32x16_bf16(v0, P[1][0], O[1][t], 0, 0, 0);
;                     O[0][t] = __builtin_amdgcn_mfma_f32_32x32x16_bf16(v1, P[0][1], O[0][t], 0, 0, 0);
;                     O[1][t] = __builtin_amdgcn_mfma_f32_32x32x16_bf16(v1, P[1][1], O[1][t], 0, 0, 0);
	v_mfma_f32_32x32x16_bf16 v[82:97], v[208:211], v[214:217], v[82:97]
	v_add_f32_e32 v213, v213, v154
	v_add_f32_e32 v213, v213, v155
	v_add_f32_e32 v213, v213, v156
	v_add_f32_e32 v213, v213, v157
	v_mfma_f32_32x32x16_bf16 v[18:33], v[208:211], v[218:221], v[18:33]
	ds_read_b64_tr_b16 v[208:209], v238 offset:28672
	ds_read_b64_tr_b16 v[210:211], v239 offset:28672
	v_exp_f32_e32 v158, v158
	v_exp_f32_e32 v159, v159
	s_waitcnt lgkmcnt(6)
	v_mfma_f32_32x32x16_bf16 v[66:81], v[230:233], v[214:217], v[66:81]
	v_exp_f32_e32 v160, v160
	v_exp_f32_e32 v161, v161
	v_mfma_f32_32x32x16_bf16 v[2:17], v[230:233], v[218:221], v[2:17]
	ds_read_b64_tr_b16 v[230:231], v250 offset:28672
	ds_read_b64_tr_b16 v[232:233], v251 offset:28672
	v_add_f32_e32 v213, v213, v158
	v_add_f32_e32 v213, v213, v159
	v_add_f32_e32 v213, v213, v160
	v_add_f32_e32 v213, v213, v161
	v_add_u32_e32 v234, s37, v234
	v_add_u32_e32 v235, s37, v235
	v_add_u32_e32 v237, s37, v237
	v_add_u32_e32 v236, s37, v236
	v_add_u32_e32 v238, s37, v238
	v_add_u32_e32 v239, s37, v239
	v_add_u32_e32 v250, s37, v250
	v_add_u32_e32 v251, s37, v251
	s_waitcnt lgkmcnt(6)
	v_mfma_f32_32x32x16_bf16 v[114:129], v[198:201], v[222:225], v[114:129]
	v_exp_f32_e32 v130, v130
	v_exp_f32_e32 v131, v131
	v_mfma_f32_32x32x16_bf16 v[50:65], v[198:201], v[226:229], v[50:65]
	v_add_u32_e32 v198, v246, v1
	ds_read_b128 v[198:201], v198 offset:8192
	v_exp_f32_e32 v132, v132
	v_exp_f32_e32 v133, v133
	s_waitcnt lgkmcnt(5)
	v_mfma_f32_32x32x16_bf16 v[98:113], v[202:205], v[222:225], v[98:113]
	v_add_f32_e32 v212, v212, v130
	v_add_f32_e32 v212, v212, v131
	v_add_f32_e32 v212, v212, v132
	v_add_f32_e32 v212, v212, v133
	v_mfma_f32_32x32x16_bf16 v[34:49], v[202:205], v[226:229], v[34:49]
	v_xad_u32 v202, v246, 32, v1
	ds_read_b128 v[202:205], v202 offset:8192
	v_exp_f32_e32 v134, v134
	v_exp_f32_e32 v135, v135
	s_waitcnt lgkmcnt(4)
	v_mfma_f32_32x32x16_bf16 v[82:97], v[208:211], v[222:225], v[82:97]
	v_exp_f32_e32 v136, v136
	v_exp_f32_e32 v137, v137
	v_mfma_f32_32x32x16_bf16 v[18:33], v[208:211], v[226:229], v[18:33]
	v_xad_u32 v208, v246, 64, v1
	ds_read_b128 v[208:211], v208 offset:8192
	v_add_f32_e32 v212, v212, v134
	v_add_f32_e32 v212, v212, v135
	v_add_f32_e32 v212, v212, v136
	v_add_f32_e32 v212, v212, v137
	s_waitcnt lgkmcnt(3)
	v_mfma_f32_32x32x16_bf16 v[66:81], v[230:233], v[222:225], v[66:81]
	v_cvt_pk_bf16_f32 v214, v146, v147
	v_cvt_pk_bf16_f32 v215, v148, v149
	v_cvt_pk_bf16_f32 v216, v150, v151
	v_cvt_pk_bf16_f32 v217, v152, v153
	v_cvt_pk_bf16_f32 v218, v130, v131
	v_cvt_pk_bf16_f32 v219, v132, v133
	v_cvt_pk_bf16_f32 v220, v134, v135
	v_cvt_pk_bf16_f32 v221, v136, v137
	v_cvt_pk_bf16_f32 v222, v154, v155
	v_cvt_pk_bf16_f32 v223, v156, v157
	v_cvt_pk_bf16_f32 v224, v158, v159
	v_cvt_pk_bf16_f32 v225, v160, v161
	v_mfma_f32_32x32x16_bf16 v[2:17], v[230:233], v[226:229], v[2:17]
	v_xad_u32 v230, v246, s47, v1
	ds_read_b128 v[230:233], v230 offset:8192
	s_add_i32 s29, s29, 1
	s_branch .Lfb_loopF
; #define LAS __attribute__((address_space(3)))
; __device__ __forceinline__ void diff_attn_phase(const Params& p, LAS unsigned char* lds) {
;     ...
;                 for (int ks = 0; ks < 4; ++ks) kf[ks] = *(const LAS bf16x8*)(Ku + kbase + (kxl ^ (32 * ks)));
;                 bf16x8 P[2][2];
; #pragma unroll
;                 for (int r = 0; r < 2; ++r) {
;                     f32x16 S;
; #pragma unroll
;                     for (int i = 0; i < 16; ++i) S[i] = 0.f;
; #pragma unroll
;                     for (int ks = 0; ks < 4; ++ks) S = __builtin_amdgcn_mfma_f32_32x32x16_bf16(kf[ks], qf[r][ks], S, 0, 0, 0);
;                     S = __builtin_amdgcn_mfma_f32_32x32x16_bf16(kone, qm[r], S, 0, 0, 0);
; #pragma unroll
;                     for (int i = 0; i < 16; ++i) S[i] = __builtin_amdgcn_exp2f(S[i]);
;                     l[r] += sum16(S);
;                     P[r][0] = pack8(S, 0); P[r][1] = pack8(S, 8);
;                 }
; #pragma unroll
;                 for (int t = 0; t < 4; ++t) {
;                     const LAS unsigned char* a0 = Vu + (vb0l ^ (64 * t)); const LAS unsigned char* a1 = Vu + (vb1l ^ (64 * t));
;                     const bf16x8 v0 = tr_pair(a0, a1), v1 = tr_pair(a0 + 4096, a1 + 4096);
;                     O[0][t] = __builtin_amdgcn_mfma_f32_32x32x16_bf16(v0, P[0][0], O[0][t], 0, 0, 0);
;                     O[1][t] = __builtin_amdgcn_mfma_f32_32x32x16_bf16(v0, P[1][0], O[1][t], 0, 0, 0);
;                     O[0][t] = __builtin_amdgcn_mfma_f32_32x32x16_bf16(v1, P[0][1], O[0][t], 0, 0, 0);
;                     O[1][t] = __builtin_amdgcn_mfma_f32_32x32x16_bf16(v1, P[1][1], O[1][t], 0, 0, 0);
;                 }
;             }
;         }
.Lfb_last0F:
	s_waitcnt lgkmcnt(6)
	v_mfma_f32_32x32x16_bf16 v[114:129], v[198:201], v[222:225], v[114:129]
	v_exp_f32_e32 v130, v130
	v_exp_f32_e32 v131, v131
	v_mfma_f32_32x32x16_bf16 v[50:65], v[198:201], v[226:229], v[50:65]
	ds_read_b64_tr_b16 v[198:199], v234 offset:24576
	ds_read_b64_tr_b16 v[200:201], v235 offset:24576
	v_exp_f32_e32 v132, v132
	v_exp_f32_e32 v133, v133
	s_waitcnt lgkmcnt(6)
	v_mfma_f32_32x32x16_bf16 v[98:113], v[202:205], v[222:225], v[98:113]
	v_add_f32_e32 v212, v212, v130
	v_add_f32_e32 v212, v212, v131
	v_add_f32_e32 v212, v212, v132
	v_add_f32_e32 v212, v212, v133
	v_mfma_f32_32x32x16_bf16 v[34:49], v[202:205], v[226:229], v[34:49]
	ds_read_b64_tr_b16 v[202:203], v237 offset:24576
	ds_read_b64_tr_b16 v[204:205], v236 offset:24576
	v_exp_f32_e32 v134, v134
	v_exp_f32_e32 v135, v135
	s_waitcnt lgkmcnt(6)
	v_mfma_f32_32x32x16_bf16 v[82:97], v[208:211], v[222:225], v[82:97]
	v_exp_f32_e32 v136, v136
	v_exp_f32_e32 v137, v137
	v_mfma_f32_32x32x16_bf16 v[18:33], v[208:211], v[226:229], v[18:33]
	ds_read_b64_tr_b16 v[208:209], v238 offset:24576
	ds_read_b64_tr_b16 v[210:211], v239 offset:24576
	v_add_f32_e32 v212, v212, v134
	v_add_f32_e32 v212, v212, v135
	v_add_f32_e32 v212, v212, v136
	v_add_f32_e32 v212, v212, v137
	s_waitcnt lgkmcnt(6)
	v_mfma_f32_32x32x16_bf16 v[66:81], v[230:233], v[222:225], v[66:81]
	v_cvt_pk_bf16_f32 v214, v146, v147
	v_cvt_pk_bf16_f32 v215, v148, v149
	v_cvt_pk_bf16_f32 v216, v150, v151
	v_cvt_pk_bf16_f32 v217, v152, v153
	v_cvt_pk_bf16_f32 v218, v130, v131
	v_cvt_pk_bf16_f32 v219, v132, v133
	v_cvt_pk_bf16_f32 v220, v134, v135
	v_cvt_pk_bf16_f32 v221, v136, v137
	v_cvt_pk_bf16_f32 v222, v154, v155
	v_cvt_pk_bf16_f32 v223, v156, v157
	v_cvt_pk_bf16_f32 v224, v158, v159
	v_cvt_pk_bf16_f32 v225, v160, v161
	v_mfma_f32_32x32x16_bf16 v[2:17], v[230:233], v[226:229], v[2:17]
	ds_read_b64_tr_b16 v[230:231], v250 offset:24576
	ds_read_b64_tr_b16 v[232:233], v251 offset:24576
	v_exp_f32_e32 v138, v138
	v_exp_f32_e32 v139, v139
	v_exp_f32_e32 v140, v140
	v_exp_f32_e32 v141, v141
	v_add_f32_e32 v212, v212, v138
	v_add_f32_e32 v212, v212, v139
	v_add_f32_e32 v212, v212, v140
	v_add_f32_e32 v212, v212, v141
	v_exp_f32_e32 v142, v142
	v_exp_f32_e32 v143, v143
	v_exp_f32_e32 v144, v144
	v_exp_f32_e32 v145, v145
	v_add_f32_e32 v212, v212, v142
	v_add_f32_e32 v212, v212, v143
	v_add_f32_e32 v212, v212, v144
	v_add_f32_e32 v212, v212, v145
	v_cvt_pk_bf16_f32 v226, v138, v139
	v_cvt_pk_bf16_f32 v227, v140, v141
	v_cvt_pk_bf16_f32 v228, v142, v143
	v_cvt_pk_bf16_f32 v229, v144, v145
	s_waitcnt lgkmcnt(6)
	v_mfma_f32_32x32x16_bf16 v[114:129], v[198:201], v[214:217], v[114:129]
	v_mfma_f32_32x32x16_bf16 v[50:65], v[198:201], v[218:221], v[50:65]
	ds_read_b64_tr_b16 v[198:199], v234 offset:28672
	ds_read_b64_tr_b16 v[200:201], v235 offset:28672
	s_waitcnt lgkmcnt(6)
	v_mfma_f32_32x32x16_bf16 v[98:113], v[202:205], v[214:217], v[98:113]
	v_mfma_f32_32x32x16_bf16 v[34:49], v[202:205], v[218:221], v[34:49]
	ds_read_b64_tr_b16 v[202:203], v237 offset:28672
	ds_read_b64_tr_b16 v[204:205], v236 offset:28672
	s_waitcnt lgkmcnt(6)
	v_mfma_f32_32x32x16_bf16 v[82:97], v[208:211], v[214:217], v[82:97]
	v_mfma_f32_32x32x16_bf16 v[18:33], v[208:211], v[218:221], v[18:33]
	ds_read_b64_tr_b16 v[208:209], v238 offset:28672
	ds_read_b64_tr_b16 v[210:211], v239 offset:28672
	s_waitcnt lgkmcnt(6)
	v_mfma_f32_32x32x16_bf16 v[66:81], v[230:233], v[214:217], v[66:81]
	v_mfma_f32_32x32x16_bf16 v[2:17], v[230:233], v[218:221], v[2:17]
	ds_read_b64_tr_b16 v[230:231], v250 offset:28672
	ds_read_b64_tr_b16 v[232:233], v251 offset:28672
	s_waitcnt lgkmcnt(6)
	v_mfma_f32_32x32x16_bf16 v[114:129], v[198:201], v[222:225], v[114:129]
	v_mfma_f32_32x32x16_bf16 v[50:65], v[198:201], v[226:229], v[50:65]
	s_waitcnt lgkmcnt(4)
	v_mfma_f32_32x32x16_bf16 v[98:113], v[202:205], v[222:225], v[98:113]
	v_mfma_f32_32x32x16_bf16 v[34:49], v[202:205], v[226:229], v[34:49]
	s_waitcnt lgkmcnt(2)
	v_mfma_f32_32x32x16_bf16 v[82:97], v[208:211], v[222:225], v[82:97]
	v_mfma_f32_32x32x16_bf16 v[18:33], v[208:211], v[226:229], v[18:33]
	s_waitcnt lgkmcnt(0)
	v_mfma_f32_32x32x16_bf16 v[66:81], v[230:233], v[222:225], v[66:81]
	v_mfma_f32_32x32x16_bf16 v[2:17], v[230:233], v[226:229], v[2:17]
	s_branch .Lad_epi
